# prep_item: Qtilde stage-2 copies written as whole 16-byte pieces from the LDS image instead of scattered 8-byte stores
# speedup vs baseline: 1.0069x; 1.0037x over previous
; #define LAS __attribute__((address_space(3)))
; __device__ __forceinline__ size_t PIX(int row, int col) { return (size_t)(col >> 7) * PSLOT + (size_t)row * 128 + (col & 127); }
; __device__ __forceinline__ int opaque_tid() { int t = threadIdx.x; asm volatile("" : "+v"(t)); return t; }
; __device__ void prep_item(const Params& p, int l, int item, LAS unsigned char* lds) {
;     const int tid = opaque_tid(), w = tid >> 6, lane = tid & 63;
;     const int tau = lane & 31, kh = lane >> 5, k0 = 16 * w + 8 * kh, l15 = lane & 15, q4 = lane >> 4;
;     const int ci = item % NCH, bh = item / NCH, h = bh & 3, b = bh >> 2;
;     const int R0 = ci < 8 ? NLAT + b * 256 + 32 * ci : b * 4096 + 32 * (ci - 8);
;     bf16_t* P = (bf16_t*)(p.ws + WS_BIG);
;     const bool first = (l == 0);
;     const bool want_out = first || ci >= 8;
;     for (int dd = 0; dd < 2; ++dd) { LAS unsigned* az = (LAS unsigned*)(lds + dd * P1_DIRSZ + P1_AW) + w * (32 * KT_ST / 2); for (int i = lane; i < 32 * KT_ST / 2; i += 64) az[i] = 0u; }
;     u32x4 rf0, rq0, rv0, rf1, rq1, rv1;
;     { const int r_ = R0 + tau; rf0 = *(const u32x4*)(P + PIX(r_, h * 128 + k0)); rq0 = *(const u32x4*)(P + PIX(r_, 1536 + h * 128 + k0)); rv0 = *(const u32x4*)(P + PIX(r_, 1024 + h * 128 + k0)); }
;     { const int r_ = R0 + 31 - tau; rf1 = *(const u32x4*)(P + PIX(r_, 512 + h * 128 + k0)); rq1 = *(const u32x4*)(P + PIX(r_, 1536 + h * 128 + k0)); rv1 = *(const u32x4*)(P + PIX(r_, 1024 + h * 128 + k0)); }
;     asm volatile("s_waitcnt vmcnt(0)" ::: "memory");
;     __syncthreads();
.LBB0_247:
	v_ashrrev_i32_e32 v1, 6, v54
	s_and_b32 s74, s6, 3
	v_lshlrev_b32_e32 v30, 4, v1
	s_lshl_b32 s6, s74, 7
	v_and_b32_e32 v31, 31, v54
	v_lshrrev_b32_e32 v0, 2, v54
	v_add_u32_e32 v3, s6, v30
	v_and_b32_e32 v0, 8, v0
	v_add_u32_e32 v2, s70, v31
	v_ashrrev_i32_e32 v4, 7, v3
	v_mov_b32_e32 v3, v8
	s_movk_i32 s0, 0x78
	v_mov_b64_e32 v[10:11], s[82:83]
	v_bitop3_b32 v6, v30, s0, v0 bitop3:0xc8
	v_mad_i64_i32 v[4:5], s[0:1], v4, s87, v[10:11]
	v_lshlrev_b64 v[36:37], 8, v[2:3]
	s_or_b32 s7, s6, 0x600
	v_lshl_add_u64 v[2:3], v[4:5], 0, v[36:37]
	v_add_u32_e32 v4, s7, v30
	v_ashrrev_i32_e32 v4, 7, v4
	v_lshlrev_b32_e32 v12, 1, v6
	v_mov_b32_e32 v13, v8
	v_mad_i64_i32 v[14:15], s[0:1], v4, s87, v[10:11]
	v_lshl_add_u64 v[2:3], v[2:3], 0, v[12:13]
	v_lshl_add_u64 v[4:5], v[14:15], 0, v[36:37]
	v_lshl_add_u64 v[16:17], v[4:5], 0, v[12:13]
	s_or_b32 s72, s6, 0x400
	s_or_b32 s71, s6, 0x200
	v_add_u32_e32 v2, s72, v30
	v_bitop3_b32 v56, v54, 31, v54 bitop3:0xc
	v_add_u32_e32 v9, s71, v30
	v_ashrrev_i32_e32 v2, 7, v2
	v_add_u32_e32 v18, s70, v56
	v_ashrrev_i32_e32 v9, 7, v9
	v_mov_b32_e32 v19, v8
	v_mad_i64_i32 v[2:3], s[0:1], v2, s87, v[10:11]
	v_mad_i64_i32 v[10:11], s[0:1], v9, s87, v[10:11]
	v_lshlrev_b64 v[32:33], 8, v[18:19]
	v_lshl_add_u64 v[16:17], v[2:3], 0, v[36:37]
	v_lshl_add_u64 v[10:11], v[10:11], 0, v[32:33]
	v_lshl_add_u64 v[16:17], v[16:17], 0, v[12:13]
	v_lshl_add_u64 v[10:11], v[10:11], 0, v[12:13]
	v_lshl_add_u64 v[10:11], v[14:15], 0, v[32:33]
	v_lshl_add_u64 v[10:11], v[10:11], 0, v[12:13]
	v_lshl_add_u64 v[2:3], v[2:3], 0, v[32:33]
	v_lshl_add_u64 v[2:3], v[2:3], 0, v[12:13]
	s_nop 0
	s_movk_i32 s0, 0xa00
	v_and_b32_e32 v57, 63, v54
	v_mul_lo_u32 v1, v1, s0
	v_readlane_b32 s1, v240, 18
	v_cndmask_b32_e64 v2, 0, 1, s[88:89]
	v_lshlrev_b32_e32 v3, 2, v57
	v_add_u32_e32 v55, 16, v1
	v_add_u32_e32 v9, s1, v1
	v_cmp_ne_u32_e64 s[40:41], 1, v2
	v_add_u32_e32 v1, v55, v3
	v_add_u32_e32 v2, v9, v3
	ds_write2st64_b32 v1, v8, v8 offset0:148 offset1:149
	ds_write2st64_b32 v1, v8, v8 offset0:150 offset1:151
	ds_write2st64_b32 v1, v8, v8 offset0:152 offset1:153
	ds_write2st64_b32 v1, v8, v8 offset0:154 offset1:155
	ds_write2st64_b32 v1, v8, v8 offset0:156 offset1:157
	ds_write2st64_b32 v2, v8, v8 offset1:1
	ds_write2st64_b32 v2, v8, v8 offset0:2 offset1:3
	ds_write2st64_b32 v2, v8, v8 offset0:4 offset1:5
	ds_write2st64_b32 v2, v8, v8 offset0:6 offset1:7
	ds_write2st64_b32 v2, v8, v8 offset0:8 offset1:9
	s_lshl_b32 s0, s74, 9
	s_waitcnt vmcnt(5)
	v_mov_b64_e32 v[156:157], v[216:217]
	v_mov_b64_e32 v[158:159], v[218:219]
	v_mov_b64_e32 v[160:161], v[220:221]
	v_mov_b64_e32 v[162:163], v[222:223]
	v_mov_b64_e32 v[168:169], v[224:225]
	v_mov_b64_e32 v[170:171], v[226:227]
	v_mov_b64_e32 v[172:173], v[228:229]
	v_mov_b64_e32 v[174:175], v[230:231]
	v_mov_b64_e32 v[4:5], v[188:189]
	v_mov_b64_e32 v[6:7], v[190:191]
	v_mov_b64_e32 v[26:27], v[192:193]
	v_mov_b64_e32 v[28:29], v[194:195]
	v_mov_b64_e32 v[22:23], v[196:197]
	v_mov_b64_e32 v[24:25], v[198:199]
	v_mov_b64_e32 v[18:19], v[200:201]
	v_mov_b64_e32 v[20:21], v[202:203]
	v_mov_b64_e32 v[14:15], v[204:205]
	v_mov_b64_e32 v[16:17], v[206:207]
	v_mov_b64_e32 v[10:11], v[208:209]
	v_mov_b64_e32 v[12:13], v[210:211]
	s_sub_i32 s98, s2, s46
	s_cmp_lt_i32 s98, 0
	s_cselect_b32 s98, s2, s98
	s_mul_hi_u32 s99, s98, 0xf0f0f0f1
	s_lshr_b32 s100, s99, 7
	s_mul_i32 s101, s100, 0x88
	s_sub_i32 s98, s98, s101
	s_lshr_b32 s99, s99, 9
	s_and_b32 s100, s100, 3
	s_lshl_b32 s101, s98, 5
	s_cmp_gt_u32 s98, 7
	s_cbranch_scc1 .Lpf_lat_b
	s_lshl_b32 s99, s99, 8
	s_add_i32 s101, s101, 0x8000
	s_branch .Lpf_join_b

; #define LAS __attribute__((address_space(3)))
; __device__ __forceinline__ size_t PIX(int row, int col) { return (size_t)(col >> 7) * PSLOT + (size_t)row * 128 + (col & 127); }
; __device__ __forceinline__ unsigned pk_bf16(float a, float b) { f32x2 v = {a, b}; bf2_t r = __builtin_convertvector(v, bf2_t); return __builtin_bit_cast(unsigned, r); }
; __device__ void prep_item(const Params& p, int l, int item, LAS unsigned char* lds) {
;     ...
;         for (int j = 0; j < 8; ++j) {
;             const float Ej = fmaxf(E[j], 1e-35f);
;             const float T0 = __builtin_bit_cast(float, __builtin_amdgcn_readlane(__builtin_bit_cast(int, Ej), 31)), T1 = __builtin_bit_cast(float, __builtin_amdgcn_readlane(__builtin_bit_cast(int, Ej), 63));
;             const float T = kh ? T1 : T0;
;             const unsigned qw = q[j >> 1]; const float qx = (j & 1) ? bf_hi(qw) : bf_lo(qw);
;             qt[j] = silu_f(qx) * 0.08838834764831845f * Ej;
;             kh_[j] = kk[j] * fast_rcp(Ej); kt_[j] = kh_[j] * T;
;             Tj[j] = T;
;         }
;         if (tau == 31) { float* dp = (float*)(p.ws + WS_DS) + ((size_t)((b * 4 + h) * 2 + dir) * NCH + ci) * 128 + k0;
;             *(f32x4*)dp = (f32x4){Tj[0], Tj[1], Tj[2], Tj[3]}; *(f32x4*)(dp + 4) = (f32x4){Tj[4], Tj[5], Tj[6], Tj[7]}; }
;         u32x4 wq, wk; wq.x = pk_bf16(qt[0], qt[1]); wq.y = pk_bf16(qt[2], qt[3]); wq.z = pk_bf16(qt[4], qt[5]); wq.w = pk_bf16(qt[6], qt[7]);
;         wk.x = pk_bf16(kh_[0], kh_[1]); wk.y = pk_bf16(kh_[2], kh_[3]); wk.z = pk_bf16(kh_[4], kh_[5]); wk.w = pk_bf16(kh_[6], kh_[7]);
;         *(LAS u32x4*)(Qs + tau * QS_ST + k0) = wq; *(LAS u32x4*)(Kh + tau * QS_ST + k0) = wk;
;         {
;           bf16_t* qd = (dir == 0) ? P + PIX(R0 + tokl, 1536 + h * 128) : (bf16_t*)(p.ws + WS_QB) + (size_t)h * PSLOT + (size_t)(R0 + tokl) * 128;
;           const int a32 = k0 & ~31, kkA = k0 & 31, kkB = kkA + 4;
;           u32x2 pa, pb; pa.x = wq.x; pa.y = wq.y; pb.x = wq.z; pb.y = wq.w;
;           *(u32x2*)(qd + a32 + 8 * ((kkA & 15) >> 2) + 4 * (kkA >> 4)) = pa;
;           *(u32x2*)(qd + a32 + 8 * ((kkB & 15) >> 2) + 4 * (kkB >> 4)) = pb; }
; #pragma unroll
;         for (int j = 0; j < 8; ++j) { Kt[(k0 + j) * KT_ST + tokl] = to_bf1(kt_[j]); const unsigned vw = v[j >> 1]; Vt[(k0 + j) * KT_ST + tau] = (bf16_t)((j & 1) ? (vw >> 16) : (vw & 0xffffu)); }
.LBB0_281:
	s_or_b64 exec, exec, s[0:1]
	v_lshlrev_b32_e32 v58, 16, v26
	v_and_b32_e32 v59, 0xffff0000, v26
	v_mul_f32_e32 v26, 0xbfb8aa3b, v58
	v_exp_f32_e32 v26, v26
	v_mul_f32_e32 v60, 0xbfb8aa3b, v59
	v_exp_f32_e32 v61, v60
	s_movk_i32 s0, 0x110
	v_add_f32_e32 v26, 1.0, v26
	v_rcp_f32_e32 v60, v26
	v_add_f32_e32 v26, 1.0, v61
	v_rcp_f32_e32 v61, v26
	v_rcp_f32_e32 v26, v52
	v_pk_mul_f32 v[58:59], v[60:61], v[58:59]
	v_lshlrev_b32_e32 v60, 16, v27
	v_and_b32_e32 v61, 0xffff0000, v27
	v_mul_f32_e32 v27, 0xbfb8aa3b, v60
	v_exp_f32_e32 v62, v27
	v_mul_f32_e32 v27, 0xbfb8aa3b, v61
	v_exp_f32_e32 v63, v27
	v_rcp_f32_e32 v27, v53
	v_add_f32_e32 v62, 1.0, v62
	v_rcp_f32_e32 v62, v62
	v_add_f32_e32 v63, 1.0, v63
	v_rcp_f32_e32 v63, v63
	v_pk_mul_f32 v[58:59], v[58:59], s[86:87] op_sel_hi:[1,0]
	s_nop 0
	v_pk_mul_f32 v[52:53], v[58:59], v[52:53]
	v_pk_mul_f32 v[58:59], v[38:39], v[26:27]
	v_pk_mul_f32 v[38:39], v[62:63], v[60:61]
	v_lshlrev_b32_e32 v60, 16, v28
	v_and_b32_e32 v61, 0xffff0000, v28
	v_mul_f32_e32 v27, 0xbfb8aa3b, v60
	v_exp_f32_e32 v28, v27
	v_mul_f32_e32 v27, 0xbfb8aa3b, v61
	v_exp_f32_e32 v63, v27
	v_rcp_f32_e32 v26, v50
	v_add_f32_e32 v28, 1.0, v28
	v_rcp_f32_e32 v62, v28
	v_add_f32_e32 v28, 1.0, v63
	v_rcp_f32_e32 v63, v28
	v_rcp_f32_e32 v27, v51
	v_pk_mul_f32 v[38:39], v[38:39], s[86:87] op_sel_hi:[1,0]
	v_lshlrev_b32_e32 v28, 16, v29
	v_pk_mul_f32 v[50:51], v[38:39], v[50:51]
	v_pk_mul_f32 v[38:39], v[62:63], v[60:61]
	v_pk_mul_f32 v[64:65], v[40:41], v[26:27]
	v_pk_mul_f32 v[38:39], v[38:39], s[86:87] op_sel_hi:[1,0]
	v_and_b32_e32 v29, 0xffff0000, v29
	v_mul_f32_e32 v27, 0xbfb8aa3b, v28
	v_pk_mul_f32 v[40:41], v[38:39], v[48:49]
	v_exp_f32_e32 v38, v27
	v_mul_f32_e32 v27, 0xbfb8aa3b, v29
	v_exp_f32_e32 v39, v27
	v_rcp_f32_e32 v26, v48
	v_rcp_f32_e32 v27, v49
	v_add_f32_e32 v38, 1.0, v38
	v_add_f32_e32 v39, 1.0, v39
	v_rcp_f32_e32 v38, v38
	v_rcp_f32_e32 v39, v39
	v_pk_mul_f32 v[44:45], v[44:45], v[26:27]
	v_rcp_f32_e32 v26, v42
	v_rcp_f32_e32 v27, v43
	v_pk_mul_f32 v[28:29], v[38:39], v[28:29]
	v_mad_u32_u24 v49, v31, s0, 16
	v_pk_mul_f32 v[28:29], v[28:29], s[86:87] op_sel_hi:[1,0]
	s_lshr_b32 s0, s7, 7
	v_pk_mul_f32 v[28:29], v[28:29], v[42:43]
	v_pk_mul_f32 v[42:43], v[46:47], v[26:27]
	v_lshlrev_b32_e32 v46, 1, v34
	s_mul_i32 s0, s0, 0x880000
	v_cvt_pk_bf16_f32 v38, v52, v53
	v_cvt_pk_bf16_f32 v39, v50, v51
	v_cvt_pk_bf16_f32 v40, v40, v41
	v_cvt_pk_bf16_f32 v41, v28, v29
	v_cvt_pk_bf16_f32 v26, v58, v59
	v_add_u32_e32 v47, v49, v46
	s_add_u32 s0, s82, s0
	v_cvt_pk_bf16_f32 v27, v64, v65
	v_cvt_pk_bf16_f32 v28, v44, v45
	v_cvt_pk_bf16_f32 v29, v42, v43
	ds_write_b128 v47, v[38:41]
	ds_write_b128 v47, v[26:29] offset:8704
	s_addc_u32 s1, s83, 0
	v_and_b32_e32 v26, 0xffffffe0, v30
	v_lshl_add_u64 v[28:29], s[0:1], 0, v[36:37]
	v_ashrrev_i32_e32 v27, 31, v26
	v_mul_f32_e32 v7, v43, v7
	v_mul_f32_e32 v6, v42, v6
	v_mul_f32_e32 v42, v59, v1
	v_mul_f32_e32 v43, v58, v0
	v_lshl_add_u64 v[0:1], v[26:27], 1, v[28:29]
	v_and_b32_e32 v28, 16, v46
	v_lshlrev_b32_e32 v28, 1, v28
	v_mov_b32_e32 v29, v8
	v_lshl_add_u64 v[0:1], v[0:1], 0, v[28:29]
	v_lshrrev_b32_e32 v29, 2, v30
	v_and_b32_e32 v29, 4, v29
	v_lshlrev_b32_e32 v36, 1, v29
	v_mov_b32_e32 v37, v8
	v_lshl_add_u64 v[0:1], v[0:1], 0, v[36:37]
	v_cvt_pk_bf16_f32 v1, v43, s0
	s_movk_i32 s0, 0x50
	v_mul_i32_i24_e32 v0, 0xfffffef2, v31
	v_mul_lo_u32 v48, v34, s0
	v_add3_u32 v0, v49, v0, v48
	v_mul_f32_e32 v2, v64, v2
	ds_write_b16 v0, v1 offset:27648
	ds_write_b16 v0, v22 offset:17408
	v_cvt_pk_bf16_f32 v1, v42, s0
	v_mul_f32_e32 v3, v65, v3
	ds_write_b16 v0, v1 offset:27728
	ds_write_b16_d16_hi v0, v22 offset:17488
	v_cvt_pk_bf16_f32 v1, v2, s0
	v_lshlrev_b32_e32 v2, 16, v18
	v_mul_f32_e32 v4, v44, v4
	ds_write_b16 v0, v1 offset:27808
	ds_write_b16 v0, v23 offset:17568
	v_cvt_pk_bf16_f32 v1, v3, s0
	v_mul_f32_e64 v3, |v2|, s69
	v_mul_f32_e32 v5, v45, v5
	ds_write_b16 v0, v1 offset:27888
	ds_write_b16_d16_hi v0, v23 offset:17648
	v_cvt_pk_bf16_f32 v1, v4, s0
	v_exp_f32_e32 v3, v3
	ds_write_b16 v0, v1 offset:27968
	ds_write_b16 v0, v24 offset:17728
	v_cvt_pk_bf16_f32 v1, v5, s0
	ds_write_b16 v0, v1 offset:28048
	ds_write_b16_d16_hi v0, v24 offset:17808
	v_cvt_pk_bf16_f32 v1, v6, s0
	ds_write_b16 v0, v1 offset:28128
	ds_write_b16 v0, v25 offset:17888
	v_cvt_pk_bf16_f32 v1, v7, s0
	ds_write_b16 v0, v1 offset:28208
	ds_write_b16_d16_hi v0, v25 offset:17968
	v_add_f32_e32 v0, 1.0, v3
	v_rcp_f32_e32 v0, v0
	s_lshl_b32 s0, s6, 2
	v_readlane_b32 s1, v243, 44
	s_add_u32 s66, s1, s0
	v_readlane_b32 s0, v243, 45
	s_addc_u32 s67, s0, 0
	v_cmp_le_f32_e64 s[0:1], 0, v2
	v_mul_f32_e32 v1, v3, v0
	s_and_b64 vcc, exec, s[40:41]
	s_mov_b64 s[40:41], -1
	s_cbranch_vccnz .LBB0_283
	v_cndmask_b32_e64 v22, v0, v1, s[0:1]
	s_mov_b64 s[40:41], 0

; #define LAS __attribute__((address_space(3)))
; __device__ __forceinline__ size_t PIX(int row, int col) { return (size_t)(col >> 7) * PSLOT + (size_t)row * 128 + (col & 127); }
; __device__ __forceinline__ unsigned pk_bf16(float a, float b) { f32x2 v = {a, b}; bf2_t r = __builtin_convertvector(v, bf2_t); return __builtin_bit_cast(unsigned, r); }
; __device__ void prep_item(const Params& p, int l, int item, LAS unsigned char* lds) {
;     ...
;         for (int j = 0; j < 8; ++j) {
;             const float Ej = fmaxf(E[j], 1e-35f);
;             const float T0 = __builtin_bit_cast(float, __builtin_amdgcn_readlane(__builtin_bit_cast(int, Ej), 31)), T1 = __builtin_bit_cast(float, __builtin_amdgcn_readlane(__builtin_bit_cast(int, Ej), 63));
;             const float T = kh ? T1 : T0;
;             const unsigned qw = q[j >> 1]; const float qx = (j & 1) ? bf_hi(qw) : bf_lo(qw);
;             qt[j] = silu_f(qx) * 0.08838834764831845f * Ej;
;             kh_[j] = kk[j] * fast_rcp(Ej); kt_[j] = kh_[j] * T;
;             Tj[j] = T;
;         }
;         if (tau == 31) { float* dp = (float*)(p.ws + WS_DS) + ((size_t)((b * 4 + h) * 2 + dir) * NCH + ci) * 128 + k0;
;             *(f32x4*)dp = (f32x4){Tj[0], Tj[1], Tj[2], Tj[3]}; *(f32x4*)(dp + 4) = (f32x4){Tj[4], Tj[5], Tj[6], Tj[7]}; }
;         u32x4 wq, wk; wq.x = pk_bf16(qt[0], qt[1]); wq.y = pk_bf16(qt[2], qt[3]); wq.z = pk_bf16(qt[4], qt[5]); wq.w = pk_bf16(qt[6], qt[7]);
;         wk.x = pk_bf16(kh_[0], kh_[1]); wk.y = pk_bf16(kh_[2], kh_[3]); wk.z = pk_bf16(kh_[4], kh_[5]); wk.w = pk_bf16(kh_[6], kh_[7]);
;         *(LAS u32x4*)(Qs + tau * QS_ST + k0) = wq; *(LAS u32x4*)(Kh + tau * QS_ST + k0) = wk;
;         {
;           bf16_t* qd = (dir == 0) ? P + PIX(R0 + tokl, 1536 + h * 128) : (bf16_t*)(p.ws + WS_QB) + (size_t)h * PSLOT + (size_t)(R0 + tokl) * 128;
;           const int a32 = k0 & ~31, kkA = k0 & 31, kkB = kkA + 4;
;           u32x2 pa, pb; pa.x = wq.x; pa.y = wq.y; pb.x = wq.z; pb.y = wq.w;
;           *(u32x2*)(qd + a32 + 8 * ((kkA & 15) >> 2) + 4 * (kkA >> 4)) = pa;
;           *(u32x2*)(qd + a32 + 8 * ((kkB & 15) >> 2) + 4 * (kkB >> 4)) = pb; }
; #pragma unroll
;         for (int j = 0; j < 8; ++j) { Kt[(k0 + j) * KT_ST + tokl] = to_bf1(kt_[j]); const unsigned vw = v[j >> 1]; Vt[(k0 + j) * KT_ST + tau] = (bf16_t)((j & 1) ? (vw >> 16) : (vw & 0xffffu)); }
;     ...
;     __syncthreads();
.LBB0_315:
	s_or_b64 exec, exec, s[0:1]
	v_lshlrev_b32_e32 v34, 16, v14
	v_and_b32_e32 v35, 0xffff0000, v14
	v_mul_f32_e32 v14, 0xbfb8aa3b, v34
	v_exp_f32_e32 v14, v14
	v_rcp_f32_e32 v50, v44
	v_rcp_f32_e32 v51, v45
	s_cmp_gt_u32 s73, 7
	v_add_f32_e32 v14, 1.0, v14
	v_rcp_f32_e32 v52, v14
	v_mul_f32_e32 v14, 0xbfb8aa3b, v35
	v_exp_f32_e32 v14, v14
	v_pk_mul_f32 v[22:23], v[22:23], v[50:51]
	v_readlane_b32 s6, v240, 28
	s_cselect_b64 s[0:1], -1, 0
	v_add_f32_e32 v14, 1.0, v14
	v_rcp_f32_e32 v53, v14
	v_rcp_f32_e32 v14, v42
	v_readlane_b32 s7, v240, 29
	v_mul_u32_u24_e32 v29, 0x110, v31
	v_pk_mul_f32 v[34:35], v[52:53], v[34:35]
	s_or_b64 s[6:7], s[6:7], s[0:1]
	v_pk_mul_f32 v[34:35], v[34:35], s[86:87] op_sel_hi:[1,0]
	v_readlane_b32 s0, v240, 19
	v_pk_mul_f32 v[34:35], v[34:35], v[44:45]
	v_lshlrev_b32_e32 v44, 16, v15
	v_and_b32_e32 v45, 0xffff0000, v15
	v_mul_f32_e32 v15, 0xbfb8aa3b, v44
	v_exp_f32_e32 v15, v15
	v_add3_u32 v29, s0, v29, v46
	s_mul_i32 s0, s74, 0x880000
	v_readlane_b32 s1, v242, 6
	v_add_f32_e32 v15, 1.0, v15
	v_rcp_f32_e32 v50, v15
	v_mul_f32_e32 v15, 0xbfb8aa3b, v45
	v_exp_f32_e32 v15, v15
	s_add_u32 s8, s1, s0
	v_readlane_b32 s1, v242, 7
	s_addc_u32 s9, s1, 0
	v_add_f32_e32 v15, 1.0, v15
	v_rcp_f32_e32 v51, v15
	v_rcp_f32_e32 v15, v43
	v_lshl_add_u64 v[32:33], s[8:9], 0, v[32:33]
	v_mov_b32_e32 v37, v8
	v_pk_mul_f32 v[44:45], v[50:51], v[44:45]
	v_readlane_b32 s1, v242, 60
	v_pk_mul_f32 v[44:45], v[44:45], s[86:87] op_sel_hi:[1,0]
	s_andn2_b64 vcc, exec, s[6:7]
	v_pk_mul_f32 v[44:45], v[44:45], v[42:43]
	v_pk_mul_f32 v[42:43], v[18:19], v[14:15]
	v_lshlrev_b32_e32 v18, 16, v16
	v_mul_f32_e32 v15, 0xbfb8aa3b, v18
	v_exp_f32_e32 v15, v15
	v_and_b32_e32 v19, 0xffff0000, v16
	v_rcp_f32_e32 v14, v40
	v_lshlrev_b32_e32 v16, 16, v17
	v_add_f32_e32 v15, 1.0, v15
	v_rcp_f32_e32 v50, v15
	v_mul_f32_e32 v15, 0xbfb8aa3b, v19
	v_exp_f32_e32 v15, v15
	v_and_b32_e32 v17, 0xffff0000, v17
	v_mul_f32_e32 v2, v42, v2
	v_mul_f32_e32 v3, v43, v3
	v_add_f32_e32 v15, 1.0, v15
	v_rcp_f32_e32 v51, v15
	v_rcp_f32_e32 v15, v41
	v_cvt_pk_bf16_f32 v2, v2, s0
	v_pk_mul_f32 v[18:19], v[50:51], v[18:19]
	v_pk_mul_f32 v[24:25], v[24:25], v[14:15]
	v_mul_f32_e32 v15, 0xbfb8aa3b, v16
	v_exp_f32_e32 v15, v15
	v_pk_mul_f32 v[18:19], v[18:19], s[86:87] op_sel_hi:[1,0]
	v_rcp_f32_e32 v14, v38
	v_pk_mul_f32 v[18:19], v[18:19], v[40:41]
	v_add_f32_e32 v15, 1.0, v15
	v_rcp_f32_e32 v40, v15
	v_mul_f32_e32 v15, 0xbfb8aa3b, v17
	v_exp_f32_e32 v15, v15
	v_cvt_pk_bf16_f32 v18, v18, v19
	v_mul_f32_e32 v4, v24, v4
	v_mul_f32_e32 v5, v25, v5
	v_add_f32_e32 v15, 1.0, v15
	v_rcp_f32_e32 v41, v15
	v_rcp_f32_e32 v15, v39
	v_pk_mul_f32 v[16:17], v[40:41], v[16:17]
	s_nop 0
	v_pk_mul_f32 v[16:17], v[16:17], s[86:87] op_sel_hi:[1,0]
	v_pk_mul_f32 v[20:21], v[20:21], v[14:15]
	v_pk_mul_f32 v[40:41], v[16:17], v[38:39]
	v_cvt_pk_bf16_f32 v38, v22, v23
	v_cvt_pk_bf16_f32 v19, v40, v41
	v_cvt_pk_bf16_f32 v39, v42, v43
	v_cvt_pk_bf16_f32 v40, v24, v25
	v_cvt_pk_bf16_f32 v41, v20, v21
	ds_write_b128 v29, v[38:41]
	v_mul_f32_e32 v7, v21, v7
	v_mul_f32_e32 v6, v20, v6
	v_mul_f32_e32 v20, v23, v1
	v_mul_f32_e32 v21, v22, v0
	v_lshl_add_u64 v[0:1], v[26:27], 1, v[32:33]
	v_mov_b32_e32 v29, v8
	v_lshl_add_u64 v[0:1], v[0:1], 0, v[28:29]
	v_cvt_pk_bf16_f32 v16, v34, v35
	v_cvt_pk_bf16_f32 v17, v44, v45
	v_lshl_add_u64 v[0:1], v[0:1], 0, v[36:37]
	ds_write_b128 v47, v[16:19] offset:58368
	v_lshlrev_b32_e32 v0, 1, v56
	v_lshlrev_b32_e32 v1, 1, v31
	v_cvt_pk_bf16_f32 v16, v21, s0
	v_add3_u32 v0, s1, v0, v48
	v_readlane_b32 s1, v240, 20
	ds_write_b16 v0, v16
	v_cvt_pk_bf16_f32 v16, v20, s0
	v_add3_u32 v1, s1, v1, v48
	ds_write_b16 v1, v10
	ds_write_b16 v0, v16 offset:80
	ds_write_b16_d16_hi v1, v10 offset:80
	ds_write_b16 v0, v2 offset:160
	ds_write_b16 v1, v11 offset:160
	v_cvt_pk_bf16_f32 v2, v3, s0
	ds_write_b16 v0, v2 offset:240
	ds_write_b16_d16_hi v1, v11 offset:240
	v_cvt_pk_bf16_f32 v2, v4, s0
	ds_write_b16 v0, v2 offset:320
	ds_write_b16 v1, v12 offset:320
	v_cvt_pk_bf16_f32 v2, v5, s0
	ds_write_b16 v0, v2 offset:400
	ds_write_b16_d16_hi v1, v12 offset:400
	v_cvt_pk_bf16_f32 v2, v6, s0
	v_and_b32_e32 v14, 15, v54
	v_lshrrev_b32_e32 v15, 4, v57
	ds_write_b16 v0, v2 offset:480
	ds_write_b16 v1, v13 offset:480
	v_cvt_pk_bf16_f32 v2, v7, s0
	ds_write_b16 v0, v2 offset:560
	ds_write_b16_d16_hi v1, v13 offset:560
	v_cndmask_b32_e64 v0, 0, 1, s[6:7]
	v_mul_u32_u24_e32 v1, 0x88, v14
	v_lshlrev_b32_e32 v18, 2, v15
	v_or_b32_e32 v2, v30, v14
	s_movk_i32 s1, 0x50
	v_cmp_ne_u32_e64 s[38:39], 1, v0
	v_lshlrev_b32_e32 v0, 3, v15
	v_lshlrev_b32_e32 v19, 4, v15
	v_lshlrev_b32_e32 v10, 1, v14
	v_mul_u32_u24_e32 v17, 0x140, v15
	v_and_b32_e32 v6, 48, v54
	v_mul_u32_u24_e32 v7, 0x50, v14
	v_ashrrev_i32_e32 v31, 31, v30
	v_lshlrev_b32_e32 v22, 1, v1
	v_cmp_gt_u32_e64 s[40:41], v14, v18
	v_or_b32_e32 v12, 1, v18
	v_or_b32_e32 v16, 2, v18
	v_or_b32_e32 v13, 3, v18
	v_mul_lo_u32 v11, v2, s1
	s_waitcnt lgkmcnt(0)
	s_barrier
; __device__ void prep_item(const Params& p, int l, int item, LAS unsigned char* lds) {
;     ...
;           bf16_t* qd = (dir == 0) ? P + PIX(R0 + tokl, 1536 + h * 128) : (bf16_t*)(p.ws + WS_QB) + (size_t)h * PSLOT + (size_t)(R0 + tokl) * 128;
;           const int a32 = k0 & ~31, kkA = k0 & 31, kkB = kkA + 4;
;           u32x2 pa, pb; pa.x = wq.x; pa.y = wq.y; pb.x = wq.z; pb.y = wq.w;
;           *(u32x2*)(qd + a32 + 8 * ((kkA & 15) >> 2) + 4 * (kkA >> 4)) = pa;
;           *(u32x2*)(qd + a32 + 8 * ((kkB & 15) >> 2) + 4 * (kkB >> 4)) = pb; }
;     ...
;     auto mfma_part = [&](const int dir) {
;         LAS unsigned char* db = lds + dir * P1_DIRSZ;
;         LAS bf16_t* Qs = (LAS bf16_t*)(db + P1_QS); LAS bf16_t* Kh = (LAS bf16_t*)(db + P1_KH);
;         LAS bf16_t* Vt = (LAS bf16_t*)(db + P1_VT); LAS bf16_t* Kt = (LAS bf16_t*)(db + P1_KT);
;         LAS bf16_t* Aw = (LAS bf16_t*)(db + P1_AW) + w * 32 * KT_ST;
;         const int tokl = dir ? 31 - tau : tau; (void)tokl;
;         if (want_out) {
;             f32x4 a00 = (f32x4){0.f, 0.f, 0.f, 0.f}, a10 = a00, a11 = a00;
; #pragma unroll
;             for (int kb = 0; kb < 4; ++kb) {
;                 const bf16x8 qn0 = *(const LAS bf16x8*)(Qs + l15 * QS_ST + 32 * kb + 8 * q4), qn1 = *(const LAS bf16x8*)(Qs + (16 + l15) * QS_ST + 32 * kb + 8 * q4);
;                 const bf16x8 kh0 = *(const LAS bf16x8*)(Kh + l15 * QS_ST + 32 * kb + 8 * q4), kh1 = *(const LAS bf16x8*)(Kh + (16 + l15) * QS_ST + 32 * kb + 8 * q4);
;                 a00 = __builtin_amdgcn_mfma_f32_16x16x32_bf16(qn0, kh0, a00, 0, 0, 0);
;                 a10 = __builtin_amdgcn_mfma_f32_16x16x32_bf16(qn1, kh0, a10, 0, 0, 0);
;                 a11 = __builtin_amdgcn_mfma_f32_16x16x32_bf16(qn1, kh1, a11, 0, 0, 0);
;             }
; #pragma unroll
;             for (int i = 0; i < 4; ++i) { const int t = 4 * q4 + i; const bool keep = l15 <= t;
;                 Aw[t * KT_ST + l15] = to_bf1(keep ? a00[i] : 0.f);
;                 Aw[(16 + t) * KT_ST + l15] = to_bf1(a10[i]);
;                 Aw[(16 + t) * KT_ST + 16 + l15] = to_bf1(keep ? a11[i] : 0.f); }
;             asm volatile("s_waitcnt lgkmcnt(0)" ::: "memory");
;             const bf16x8 vf = *(const LAS bf16x8*)(Vt + (16 * w + l15) * KT_ST + 8 * q4);
;             bf16_t* OFB = (bf16_t*)(p.ws + WS_OFB) + (size_t)dir * NROW * 512;
; #pragma unroll
;             for (int mt = 0; mt < 2; ++mt) {
	v_lshrrev_b32_e32 v140, 4, v135
	v_and_b32_e32 v141, 15, v135
	v_lshrrev_b32_e32 v142, 2, v141
	v_and_b32_e32 v143, 3, v141
	v_mul_u32_u24_e32 v144, 0x110, v140
	v_lshl_add_u32 v144, v142, 6, v144
	v_lshl_add_u32 v144, v143, 3, v144
	ds_read_b64 v[232:233], v144 offset:16
	ds_read_b64 v[234:235], v144 offset:48
	ds_read_b64 v[236:237], v144 offset:58384
	ds_read_b64 v[238:239], v144 offset:58416
	v_lshlrev_b32_e32 v145, 8, v140
	v_lshl_add_u32 v145, v141, 4, v145
	v_sub_u32_e32 v146, 31, v140
	v_lshlrev_b32_e32 v146, 8, v146
	v_lshl_add_u32 v146, v141, 4, v146
	s_lshr_b32 s98, s72, 7
	s_add_i32 s99, s98, 4
	s_mul_i32 s99, s99, 0x880000
	s_lshl_b32 s100, s70, 8
	s_add_u32 s99, s99, s100
	s_add_u32 s18, s82, s99
	s_addc_u32 s19, s83, 0
	s_add_i32 s98, s98, -8
	s_mul_i32 s98, s98, 0x880000
	s_add_u32 s98, s98, s100
	s_add_u32 s98, s98, 0x1b1ad000
	s_add_u32 s20, s62, s98
	s_addc_u32 s21, s63, 0
	s_waitcnt lgkmcnt(0)
	global_store_dwordx4 v145, v[232:235], s[18:19]
	global_store_dwordx4 v146, v[236:239], s[20:21]
	s_cbranch_vccnz .LBB0_317
	v_add3_u32 v1, 16, v22, v19
	ds_read_b128 v[2:5], v1
	ds_read_b128 v[24:27], v1 offset:4352
	ds_read_b128 v[32:35], v1 offset:8704
	ds_read_b128 v[36:39], v1 offset:13056
	s_movk_i32 s1, 0x140
	v_cmp_gt_u32_e32 vcc, v14, v12
	v_add3_u32 v23, v55, v7, v6
	s_waitcnt lgkmcnt(1)
	v_mfma_f32_16x16x32_bf16 v[2:5], v[2:5], v[32:35], 0
	v_readlane_b32 s6, v242, 8
	v_readlane_b32 s7, v242, 9
	s_add_u32 s6, s6, s0
	v_mfma_f32_16x16x32_bf16 v[32:35], v[24:27], v[32:35], 0
	v_add_u32_e32 v28, s70, v14
	v_mov_b32_e32 v29, v8
	s_addc_u32 s7, s7, 0
	s_waitcnt lgkmcnt(0)
	v_mfma_f32_16x16x32_bf16 v[24:27], v[24:27], v[36:39], 0
	ds_read_b128 v[36:39], v1 offset:64
	ds_read_b128 v[40:43], v1 offset:4416
	ds_read_b128 v[44:47], v1 offset:8768
	ds_read_b128 v[48:51], v1 offset:13120
	s_waitcnt lgkmcnt(1)
	v_mfma_f32_16x16x32_bf16 v[2:5], v[36:39], v[44:47], v[2:5]
	v_mfma_f32_16x16x32_bf16 v[32:35], v[40:43], v[44:47], v[32:35]
	s_waitcnt lgkmcnt(0)
	v_mfma_f32_16x16x32_bf16 v[24:27], v[40:43], v[48:51], v[24:27]
	ds_read_b128 v[36:39], v1 offset:128
	ds_read_b128 v[40:43], v1 offset:4480
	ds_read_b128 v[44:47], v1 offset:8832
	ds_read_b128 v[48:51], v1 offset:13184
	s_waitcnt lgkmcnt(1)
	v_mfma_f32_16x16x32_bf16 v[2:5], v[36:39], v[44:47], v[2:5]
	v_mfma_f32_16x16x32_bf16 v[32:35], v[40:43], v[44:47], v[32:35]
	s_waitcnt lgkmcnt(0)
	v_mfma_f32_16x16x32_bf16 v[24:27], v[40:43], v[48:51], v[24:27]
	ds_read_b128 v[36:39], v1 offset:192
	ds_read_b128 v[40:43], v1 offset:4544
	ds_read_b128 v[44:47], v1 offset:8896
	ds_read_b128 v[48:51], v1 offset:13248
	v_add_u32_e32 v1, v55, v10
	v_mad_u32_u24 v20, v15, s1, v1
	s_waitcnt lgkmcnt(1)
	v_mfma_f32_16x16x32_bf16 v[2:5], v[36:39], v[44:47], v[2:5]
	s_movk_i32 s1, 0x50
	v_mfma_f32_16x16x32_bf16 v[32:35], v[40:43], v[44:47], v[32:35]
	s_nop 5
	v_cvt_pk_bf16_f32 v2, v2, s0
	v_cndmask_b32_e64 v2, v2, 0, s[40:41]
	ds_write_b16 v20, v2 offset:37888
	s_waitcnt lgkmcnt(1)
	v_mfma_f32_16x16x32_bf16 v[24:27], v[40:43], v[48:51], v[24:27]
	v_add3_u32 v20, v55, v17, v10
	v_cvt_pk_bf16_f32 v2, v32, s0
	ds_write_b16 v20, v2 offset:39168
	s_nop 4
	v_cvt_pk_bf16_f32 v2, v24, s0
	v_cndmask_b32_e64 v2, v2, 0, s[40:41]
	ds_write_b16 v20, v2 offset:39200
	v_cvt_pk_bf16_f32 v2, v3, s0
	v_cndmask_b32_e64 v2, v2, 0, vcc
	v_mul_u32_u24_e32 v3, 0x50, v12
	v_mad_u32_u24 v20, v12, s1, v1
	ds_write_b16 v20, v2 offset:37888
	v_cvt_pk_bf16_f32 v2, v33, s0
	v_add3_u32 v3, v55, v3, v10
	ds_write_b16 v3, v2 offset:39168
	v_cvt_pk_bf16_f32 v2, v25, s0
	v_cndmask_b32_e64 v2, v2, 0, vcc
	ds_write_b16 v3, v2 offset:39200
	v_cmp_gt_u32_e32 vcc, v14, v16
	v_cvt_pk_bf16_f32 v2, v4, s0
	v_mad_u32_u24 v3, v12, s1, s1
	v_cndmask_b32_e64 v2, v2, 0, vcc
	v_add_u32_e32 v4, v1, v3
	ds_write_b16 v4, v2 offset:37888
	v_cvt_pk_bf16_f32 v2, v34, s0
	v_add3_u32 v3, v55, v3, v10
	ds_write_b16 v3, v2 offset:39168
	v_cvt_pk_bf16_f32 v2, v26, s0
	v_cndmask_b32_e64 v2, v2, 0, vcc
	ds_write_b16 v3, v2 offset:39200
	v_cmp_gt_u32_e32 vcc, v14, v13
	v_cvt_pk_bf16_f32 v2, v5, s0
	v_mad_u32_u24 v3, v12, s1, v186
	v_cndmask_b32_e64 v2, v2, 0, vcc
	v_add_u32_e32 v1, v1, v3
	ds_write_b16 v1, v2 offset:37888
	v_cvt_pk_bf16_f32 v1, v35, s0
	v_add3_u32 v2, v55, v3, v10
	ds_write_b16 v2, v1 offset:39168
	v_cvt_pk_bf16_f32 v1, v27, s0
	v_cndmask_b32_e64 v1, v1, 0, vcc
	ds_write_b16 v2, v1 offset:39200
	s_waitcnt lgkmcnt(0)
	v_add3_u32 v1, 16, v11, v6
	ds_read_b128 v[2:5], v1 offset:17408
	ds_read_b128 v[24:27], v23 offset:37888
	s_waitcnt lgkmcnt(0)
	v_mfma_f32_16x16x32_bf16 v[24:27], v[2:5], v[24:27], 0
	v_lshlrev_b64 v[32:33], 1, v[30:31]
	v_mov_b32_e32 v1, v8
	s_nop 5
	v_cvt_pk_bf16_f32 v20, v24, v25
	v_lshlrev_b64 v[24:25], 8, v[28:29]
	v_lshl_add_u64 v[24:25], s[6:7], 0, v[24:25]
	v_lshl_add_u64 v[24:25], v[24:25], 0, v[32:33]
	v_cvt_pk_bf16_f32 v21, v26, v27
	v_lshl_add_u64 v[24:25], v[24:25], 0, v[0:1]
	global_store_dwordx2 v[24:25], v[20:21], off
	ds_read_b128 v[24:27], v23 offset:39168
	s_waitcnt lgkmcnt(0)
	v_mfma_f32_16x16x32_bf16 v[2:5], v[2:5], v[24:27], 0
	s_nop 7
	v_cvt_pk_bf16_f32 v2, v2, v3
	v_cvt_pk_bf16_f32 v3, v4, v5
	v_add_u32_e32 v4, 16, v28
	v_mov_b32_e32 v5, v8
	v_lshlrev_b64 v[4:5], 8, v[4:5]
	v_lshl_add_u64 v[4:5], s[6:7], 0, v[4:5]
	v_lshl_add_u64 v[4:5], v[4:5], 0, v[32:33]
	v_lshl_add_u64 v[4:5], v[4:5], 0, v[0:1]
	global_store_dwordx2 v[4:5], v[2:3], off
